# barrier L1 invalidate issued right behind the arrival atomic's return (overlaps the last arriver's L2 write-back)
# baseline (speedup 1.0000x reference)
; __device__ __forceinline__ unsigned xb_ld(unsigned* p)              { return __hip_atomic_load(p, __ATOMIC_RELAXED, __HIP_MEMORY_SCOPE_AGENT); }
; __device__ __forceinline__ unsigned xb_add(unsigned* p, unsigned v) { return __hip_atomic_fetch_add(p, v, __ATOMIC_RELAXED, __HIP_MEMORY_SCOPE_AGENT); }
; #define XB_SPIN(cond, bar) do { unsigned _sp = 0; while (cond) { __builtin_amdgcn_s_sleep(1); \
;     if ((++_sp & 255u) == 0u) { if (xb_ld(&(bar)[XB_TMO])) break; if (_sp > XB_SPIN_CAP) { atomicAdd(&(bar)[XB_TMO], 1u); break; } } } } while (0)
; __device__ __forceinline__ void xcd_barrier(const XcdBarrier& b) {
;     ...
;     if (threadIdx.x == 0) {
;         unsigned* bar = b.bar;
;         __builtin_amdgcn_s_waitcnt(0);
;         unsigned nloc = b.st[0], nx = b.st[1];
;         if (nloc == 0u) { xcd_barrier_complete(bar, b.x, nloc, nx); b.st[0] = nloc; b.st[1] = nx; }
;         const unsigned old = xb_add(&bar[XB_XSUB(b.x)], 1u);
;         const unsigned gen = old / nloc;
;         if (old + 1u == (gen + 1u) * nloc) {
;             __builtin_amdgcn_fence(__ATOMIC_RELEASE, "agent");
;             asm volatile("s_waitcnt vmcnt(0)" ::: "memory");
;             const unsigned og = xb_add(&bar[XB_TOP], 1u);
;             const unsigned tg = og / nx;
;             if (og + 1u == (tg + 1u) * nx) xb_add(&bar[XB_TOPGEN], 1u);
;             else XB_SPIN(xb_ld(&bar[XB_TOPGEN]) == tg, bar);
;             __builtin_amdgcn_fence(__ATOMIC_ACQUIRE, "agent");
;             xb_add(&bar[XB_XGEN(b.x)], 1u);
;             asm volatile("s_waitcnt vmcnt(0)" ::: "memory");
;         } else {
;             XB_SPIN(xb_ld(&bar[XB_XGEN(b.x)]) == gen, bar);
.LBB0_70:
	s_lshl_b32 s3, s33, 8
	s_add_u32 s6, s38, s3
	s_addc_u32 s7, s39, 0
	v_mov_b32_e32 v2, 0x1000
	v_mov_b32_e32 v4, 1
	global_atomic_add v4, v2, v4, s[6:7] offset:1024 sc0
	v_cvt_f32_u32_e32 v2, v3
	v_sub_u32_e32 v5, 0, v3
	v_rcp_iflag_f32_e32 v2, v2
	s_nop 0
	v_mul_f32_e32 v2, 0x4f7ffffe, v2
	v_cvt_u32_f32_e32 v2, v2
	v_mul_lo_u32 v5, v5, v2
	v_mul_hi_u32 v5, v2, v5
	v_add_u32_e32 v2, v2, v5
	s_waitcnt vmcnt(0)
	buffer_inv sc1
	v_mul_hi_u32 v2, v4, v2
	v_mul_lo_u32 v5, v2, v3
	v_sub_u32_e32 v5, v4, v5
	v_add_u32_e32 v6, 1, v2
	v_cmp_ge_u32_e32 vcc, v5, v3
	v_add_u32_e32 v4, 1, v4
	s_nop 0
	v_cndmask_b32_e32 v2, v2, v6, vcc
	v_sub_u32_e32 v6, v5, v3
	v_cndmask_b32_e32 v5, v5, v6, vcc
	v_add_u32_e32 v6, 1, v2
	v_cmp_ge_u32_e32 vcc, v5, v3
	s_nop 1
	v_cndmask_b32_e32 v2, v2, v6, vcc
	v_mul_lo_u32 v5, v3, v2
	v_add_u32_e32 v3, v5, v3
	v_cmp_ne_u32_e32 vcc, v4, v3
	s_and_saveexec_b64 s[14:15], vcc
	s_xor_b64 s[14:15], exec, s[14:15]
	s_cbranch_execz .LBB0_84
	s_waitcnt lgkmcnt(0)
	v_mov_b32_e32 v1, 0x2000
	global_load_dword v1, v1, s[6:7] offset:1024 sc1
	s_add_u32 s20, s6, 0x2400
	s_addc_u32 s21, s7, 0
	s_waitcnt vmcnt(0)
	v_cmp_eq_u32_e32 vcc, v1, v2
	s_and_saveexec_b64 s[16:17], vcc
	s_cbranch_execz .LBB0_83
	s_add_u32 s18, s54, 0x4200
	s_addc_u32 s19, s55, 0
	s_mov_b32 s3, 1
	s_mov_b64 s[22:23], 0
	v_mov_b32_e32 v1, 0
	s_branch .LBB0_74

; __device__ __forceinline__ unsigned xb_ld(unsigned* p)              { return __hip_atomic_load(p, __ATOMIC_RELAXED, __HIP_MEMORY_SCOPE_AGENT); }
; __device__ __forceinline__ unsigned xb_add(unsigned* p, unsigned v) { return __hip_atomic_fetch_add(p, v, __ATOMIC_RELAXED, __HIP_MEMORY_SCOPE_AGENT); }
; #define XB_SPIN(cond, bar) do { unsigned _sp = 0; while (cond) { __builtin_amdgcn_s_sleep(1); \
;     if ((++_sp & 255u) == 0u) { if (xb_ld(&(bar)[XB_TMO])) break; if (_sp > XB_SPIN_CAP) { atomicAdd(&(bar)[XB_TMO], 1u); break; } } } } while (0)
; __device__ __forceinline__ void xcd_barrier(const XcdBarrier& b) {
;     ...
;     if (threadIdx.x == 0) {
;         unsigned* bar = b.bar;
;         __builtin_amdgcn_s_waitcnt(0);
;         unsigned nloc = b.st[0], nx = b.st[1];
;         if (nloc == 0u) { xcd_barrier_complete(bar, b.x, nloc, nx); b.st[0] = nloc; b.st[1] = nx; }
;         const unsigned old = xb_add(&bar[XB_XSUB(b.x)], 1u);
;         const unsigned gen = old / nloc;
;         if (old + 1u == (gen + 1u) * nloc) {
;             __builtin_amdgcn_fence(__ATOMIC_RELEASE, "agent");
;             asm volatile("s_waitcnt vmcnt(0)" ::: "memory");
;             const unsigned og = xb_add(&bar[XB_TOP], 1u);
;             const unsigned tg = og / nx;
;             if (og + 1u == (tg + 1u) * nx) xb_add(&bar[XB_TOPGEN], 1u);
;             else XB_SPIN(xb_ld(&bar[XB_TOPGEN]) == tg, bar);
;             __builtin_amdgcn_fence(__ATOMIC_ACQUIRE, "agent");
;             xb_add(&bar[XB_XGEN(b.x)], 1u);
;             asm volatile("s_waitcnt vmcnt(0)" ::: "memory");
;         } else {
;             XB_SPIN(xb_ld(&bar[XB_XGEN(b.x)]) == gen, bar);
.LBB0_338:
	s_lshl_b32 s3, s33, 8
	s_add_u32 s4, s38, s3
	s_addc_u32 s5, s39, 0
	v_mov_b32_e32 v2, 0x1000
	v_mov_b32_e32 v4, 1
	global_atomic_add v4, v2, v4, s[4:5] offset:1024 sc0
	v_cvt_f32_u32_e32 v2, v3
	v_sub_u32_e32 v5, 0, v3
	v_rcp_iflag_f32_e32 v2, v2
	s_nop 0
	v_mul_f32_e32 v2, 0x4f7ffffe, v2
	v_cvt_u32_f32_e32 v2, v2
	v_mul_lo_u32 v5, v5, v2
	v_mul_hi_u32 v5, v2, v5
	v_add_u32_e32 v2, v2, v5
	s_waitcnt vmcnt(0)
	buffer_inv sc1
	v_mul_hi_u32 v2, v4, v2
	v_mul_lo_u32 v5, v2, v3
	v_sub_u32_e32 v5, v4, v5
	v_add_u32_e32 v6, 1, v2
	v_cmp_ge_u32_e32 vcc, v5, v3
	v_add_u32_e32 v4, 1, v4
	s_nop 0
	v_cndmask_b32_e32 v2, v2, v6, vcc
	v_sub_u32_e32 v6, v5, v3
	v_cndmask_b32_e32 v5, v5, v6, vcc
	v_add_u32_e32 v6, 1, v2
	v_cmp_ge_u32_e32 vcc, v5, v3
	s_nop 1
	v_cndmask_b32_e32 v2, v2, v6, vcc
	v_mul_lo_u32 v5, v3, v2
	v_add_u32_e32 v3, v5, v3
	v_cmp_ne_u32_e32 vcc, v4, v3
	s_and_saveexec_b64 s[14:15], vcc
	s_xor_b64 s[14:15], exec, s[14:15]
	s_cbranch_execz .LBB0_352
	s_waitcnt lgkmcnt(0)
	v_mov_b32_e32 v1, 0x2000
	global_load_dword v1, v1, s[4:5] offset:1024 sc1
	s_add_u32 s20, s4, 0x2400
	s_addc_u32 s21, s5, 0
	s_waitcnt vmcnt(0)
	v_cmp_eq_u32_e32 vcc, v1, v2
	s_and_saveexec_b64 s[16:17], vcc
	s_cbranch_execz .LBB0_351
	s_add_u32 s18, s54, 0x4200
	s_addc_u32 s19, s55, 0
	s_mov_b32 s3, 1
	s_mov_b64 s[22:23], 0
	v_mov_b32_e32 v1, 0
	s_branch .LBB0_342

; __device__ __forceinline__ unsigned xb_ld(unsigned* p)              { return __hip_atomic_load(p, __ATOMIC_RELAXED, __HIP_MEMORY_SCOPE_AGENT); }
; __device__ __forceinline__ unsigned xb_add(unsigned* p, unsigned v) { return __hip_atomic_fetch_add(p, v, __ATOMIC_RELAXED, __HIP_MEMORY_SCOPE_AGENT); }
; #define XB_SPIN(cond, bar) do { unsigned _sp = 0; while (cond) { __builtin_amdgcn_s_sleep(1); \
;     if ((++_sp & 255u) == 0u) { if (xb_ld(&(bar)[XB_TMO])) break; if (_sp > XB_SPIN_CAP) { atomicAdd(&(bar)[XB_TMO], 1u); break; } } } } while (0)
; __device__ __forceinline__ void xcd_barrier(const XcdBarrier& b) {
;     ...
;     if (threadIdx.x == 0) {
;         unsigned* bar = b.bar;
;         __builtin_amdgcn_s_waitcnt(0);
;         unsigned nloc = b.st[0], nx = b.st[1];
;         if (nloc == 0u) { xcd_barrier_complete(bar, b.x, nloc, nx); b.st[0] = nloc; b.st[1] = nx; }
;         const unsigned old = xb_add(&bar[XB_XSUB(b.x)], 1u);
;         const unsigned gen = old / nloc;
;         if (old + 1u == (gen + 1u) * nloc) {
;             __builtin_amdgcn_fence(__ATOMIC_RELEASE, "agent");
;             asm volatile("s_waitcnt vmcnt(0)" ::: "memory");
;             const unsigned og = xb_add(&bar[XB_TOP], 1u);
;             const unsigned tg = og / nx;
;             if (og + 1u == (tg + 1u) * nx) xb_add(&bar[XB_TOPGEN], 1u);
;             else XB_SPIN(xb_ld(&bar[XB_TOPGEN]) == tg, bar);
;             __builtin_amdgcn_fence(__ATOMIC_ACQUIRE, "agent");
;             xb_add(&bar[XB_XGEN(b.x)], 1u);
;             asm volatile("s_waitcnt vmcnt(0)" ::: "memory");
;         } else {
;             XB_SPIN(xb_ld(&bar[XB_XGEN(b.x)]) == gen, bar);
.LBB0_440:
	s_lshl_b32 s3, s33, 8
	s_add_u32 s4, s38, s3
	s_addc_u32 s5, s39, 0
	v_mov_b32_e32 v2, 0x1000
	v_mov_b32_e32 v4, 1
	global_atomic_add v4, v2, v4, s[4:5] offset:1024 sc0
	v_cvt_f32_u32_e32 v2, v3
	v_sub_u32_e32 v5, 0, v3
	v_rcp_iflag_f32_e32 v2, v2
	s_nop 0
	v_mul_f32_e32 v2, 0x4f7ffffe, v2
	v_cvt_u32_f32_e32 v2, v2
	v_mul_lo_u32 v5, v5, v2
	v_mul_hi_u32 v5, v2, v5
	v_add_u32_e32 v2, v2, v5
	s_waitcnt vmcnt(0)
	buffer_inv sc1
	v_mul_hi_u32 v2, v4, v2
	v_mul_lo_u32 v5, v2, v3
	v_sub_u32_e32 v5, v4, v5
	v_add_u32_e32 v6, 1, v2
	v_cmp_ge_u32_e32 vcc, v5, v3
	v_add_u32_e32 v4, 1, v4
	s_nop 0
	v_cndmask_b32_e32 v2, v2, v6, vcc
	v_sub_u32_e32 v6, v5, v3
	v_cndmask_b32_e32 v5, v5, v6, vcc
	v_add_u32_e32 v6, 1, v2
	v_cmp_ge_u32_e32 vcc, v5, v3
	s_nop 1
	v_cndmask_b32_e32 v2, v2, v6, vcc
	v_mul_lo_u32 v5, v3, v2
	v_add_u32_e32 v3, v5, v3
	v_cmp_ne_u32_e32 vcc, v4, v3
	s_and_saveexec_b64 s[6:7], vcc
	s_xor_b64 s[6:7], exec, s[6:7]
	s_cbranch_execz .LBB0_454
	s_waitcnt lgkmcnt(0)
	v_mov_b32_e32 v1, 0x2000
	global_load_dword v1, v1, s[4:5] offset:1024 sc1
	s_add_u32 s18, s4, 0x2400
	s_addc_u32 s19, s5, 0
	s_waitcnt vmcnt(0)
	v_cmp_eq_u32_e32 vcc, v1, v2
	s_and_saveexec_b64 s[14:15], vcc
	s_cbranch_execz .LBB0_453
	s_add_u32 s16, s54, 0x4200
	s_addc_u32 s17, s55, 0
	s_mov_b32 s3, 1
	s_mov_b64 s[20:21], 0
	v_mov_b32_e32 v1, 0
	s_branch .LBB0_444

; __device__ __forceinline__ unsigned xb_ld(unsigned* p)              { return __hip_atomic_load(p, __ATOMIC_RELAXED, __HIP_MEMORY_SCOPE_AGENT); }
; __device__ __forceinline__ unsigned xb_add(unsigned* p, unsigned v) { return __hip_atomic_fetch_add(p, v, __ATOMIC_RELAXED, __HIP_MEMORY_SCOPE_AGENT); }
; #define XB_SPIN(cond, bar) do { unsigned _sp = 0; while (cond) { __builtin_amdgcn_s_sleep(1); \
;     if ((++_sp & 255u) == 0u) { if (xb_ld(&(bar)[XB_TMO])) break; if (_sp > XB_SPIN_CAP) { atomicAdd(&(bar)[XB_TMO], 1u); break; } } } } while (0)
; __device__ __forceinline__ void xcd_barrier(const XcdBarrier& b) {
;     ...
;     if (threadIdx.x == 0) {
;         unsigned* bar = b.bar;
;         __builtin_amdgcn_s_waitcnt(0);
;         unsigned nloc = b.st[0], nx = b.st[1];
;         if (nloc == 0u) { xcd_barrier_complete(bar, b.x, nloc, nx); b.st[0] = nloc; b.st[1] = nx; }
;         const unsigned old = xb_add(&bar[XB_XSUB(b.x)], 1u);
;         const unsigned gen = old / nloc;
;         if (old + 1u == (gen + 1u) * nloc) {
;             __builtin_amdgcn_fence(__ATOMIC_RELEASE, "agent");
;             asm volatile("s_waitcnt vmcnt(0)" ::: "memory");
;             const unsigned og = xb_add(&bar[XB_TOP], 1u);
;             const unsigned tg = og / nx;
;             if (og + 1u == (tg + 1u) * nx) xb_add(&bar[XB_TOPGEN], 1u);
;             else XB_SPIN(xb_ld(&bar[XB_TOPGEN]) == tg, bar);
;             __builtin_amdgcn_fence(__ATOMIC_ACQUIRE, "agent");
;             xb_add(&bar[XB_XGEN(b.x)], 1u);
;             asm volatile("s_waitcnt vmcnt(0)" ::: "memory");
;         } else {
;             XB_SPIN(xb_ld(&bar[XB_XGEN(b.x)]) == gen, bar);
.LBB0_553:
	v_readlane_b32 s4, v245, 48
	v_readlane_b32 s5, v245, 49
	v_cvt_f32_u32_e32 v2, v5
	v_sub_u32_e32 v7, 0, v5
	v_rcp_iflag_f32_e32 v2, v2
	s_nop 1
	global_atomic_add v6, v3, v213, s[4:5] sc0
	v_mul_f32_e32 v2, 0x4f7ffffe, v2
	v_cvt_u32_f32_e32 v2, v2
	v_mul_lo_u32 v7, v7, v2
	v_mul_hi_u32 v7, v2, v7
	v_add_u32_e32 v2, v2, v7
	s_waitcnt vmcnt(0)
	buffer_inv sc1
	v_mul_hi_u32 v2, v6, v2
	v_mul_lo_u32 v7, v2, v5
	v_sub_u32_e32 v7, v6, v7
	v_add_u32_e32 v8, 1, v2
	v_cmp_ge_u32_e32 vcc, v7, v5
	v_add_u32_e32 v6, 1, v6
	s_nop 0
	v_cndmask_b32_e32 v2, v2, v8, vcc
	v_sub_u32_e32 v8, v7, v5
	v_cndmask_b32_e32 v7, v7, v8, vcc
	v_add_u32_e32 v8, 1, v2
	v_cmp_ge_u32_e32 vcc, v7, v5
	s_nop 1
	v_cndmask_b32_e32 v2, v2, v8, vcc
	v_mul_lo_u32 v7, v5, v2
	v_add_u32_e32 v5, v7, v5
	v_cmp_ne_u32_e32 vcc, v6, v5
	s_and_saveexec_b64 s[4:5], vcc
	s_xor_b64 s[4:5], exec, s[4:5]
	s_cbranch_execz .LBB0_567
	v_readlane_b32 s6, v245, 50
	v_readlane_b32 s7, v245, 51
	s_waitcnt lgkmcnt(0)
	s_nop 3
	global_load_dword v4, v3, s[6:7] sc1
	s_waitcnt vmcnt(0)
	v_cmp_eq_u32_e32 vcc, v4, v2
	s_and_saveexec_b64 s[6:7], vcc
	s_cbranch_execz .LBB0_566
	s_mov_b32 s25, 1
	s_mov_b64 s[14:15], 0
	s_branch .LBB0_557

; __device__ __forceinline__ unsigned xb_ld(unsigned* p)              { return __hip_atomic_load(p, __ATOMIC_RELAXED, __HIP_MEMORY_SCOPE_AGENT); }
; __device__ __forceinline__ unsigned xb_add(unsigned* p, unsigned v) { return __hip_atomic_fetch_add(p, v, __ATOMIC_RELAXED, __HIP_MEMORY_SCOPE_AGENT); }
; #define XB_SPIN(cond, bar) do { unsigned _sp = 0; while (cond) { __builtin_amdgcn_s_sleep(1); \
;     if ((++_sp & 255u) == 0u) { if (xb_ld(&(bar)[XB_TMO])) break; if (_sp > XB_SPIN_CAP) { atomicAdd(&(bar)[XB_TMO], 1u); break; } } } } while (0)
; __device__ __forceinline__ void xcd_barrier(const XcdBarrier& b) {
;     ...
;     if (threadIdx.x == 0) {
;         unsigned* bar = b.bar;
;         __builtin_amdgcn_s_waitcnt(0);
;         unsigned nloc = b.st[0], nx = b.st[1];
;         if (nloc == 0u) { xcd_barrier_complete(bar, b.x, nloc, nx); b.st[0] = nloc; b.st[1] = nx; }
;         const unsigned old = xb_add(&bar[XB_XSUB(b.x)], 1u);
;         const unsigned gen = old / nloc;
;         if (old + 1u == (gen + 1u) * nloc) {
;             __builtin_amdgcn_fence(__ATOMIC_RELEASE, "agent");
;             asm volatile("s_waitcnt vmcnt(0)" ::: "memory");
;             const unsigned og = xb_add(&bar[XB_TOP], 1u);
;             const unsigned tg = og / nx;
;             if (og + 1u == (tg + 1u) * nx) xb_add(&bar[XB_TOPGEN], 1u);
;             else XB_SPIN(xb_ld(&bar[XB_TOPGEN]) == tg, bar);
;             __builtin_amdgcn_fence(__ATOMIC_ACQUIRE, "agent");
;             xb_add(&bar[XB_XGEN(b.x)], 1u);
;             asm volatile("s_waitcnt vmcnt(0)" ::: "memory");
;         } else {
;             XB_SPIN(xb_ld(&bar[XB_XGEN(b.x)]) == gen, bar);
.LBB0_2328:
	v_readlane_b32 s4, v245, 48
	v_readlane_b32 s5, v245, 49
	v_cvt_f32_u32_e32 v2, v5
	v_sub_u32_e32 v7, 0, v5
	v_rcp_iflag_f32_e32 v2, v2
	s_nop 1
	global_atomic_add v6, v3, v213, s[4:5] sc0
	v_mul_f32_e32 v2, 0x4f7ffffe, v2
	v_cvt_u32_f32_e32 v2, v2
	v_mul_lo_u32 v7, v7, v2
	v_mul_hi_u32 v7, v2, v7
	v_add_u32_e32 v2, v2, v7
	s_waitcnt vmcnt(0)
	buffer_inv sc1
	v_mul_hi_u32 v2, v6, v2
	v_mul_lo_u32 v7, v2, v5
	v_sub_u32_e32 v7, v6, v7
	v_add_u32_e32 v8, 1, v2
	v_cmp_ge_u32_e32 vcc, v7, v5
	v_add_u32_e32 v6, 1, v6
	s_nop 0
	v_cndmask_b32_e32 v2, v2, v8, vcc
	v_sub_u32_e32 v8, v7, v5
	v_cndmask_b32_e32 v7, v7, v8, vcc
	v_add_u32_e32 v8, 1, v2
	v_cmp_ge_u32_e32 vcc, v7, v5
	s_nop 1
	v_cndmask_b32_e32 v2, v2, v8, vcc
	v_mul_lo_u32 v7, v5, v2
	v_add_u32_e32 v5, v7, v5
	v_cmp_ne_u32_e32 vcc, v6, v5
	s_and_saveexec_b64 s[4:5], vcc
	s_xor_b64 s[4:5], exec, s[4:5]
	s_cbranch_execz .LBB0_2342
	v_readlane_b32 s6, v245, 50
	v_readlane_b32 s7, v245, 51
	s_waitcnt lgkmcnt(0)
	s_nop 3
	global_load_dword v4, v3, s[6:7] sc1
	s_waitcnt vmcnt(0)
	v_cmp_eq_u32_e32 vcc, v4, v2
	s_and_saveexec_b64 s[6:7], vcc
	s_cbranch_execz .LBB0_2341
	s_mov_b32 s24, 1
	s_mov_b64 s[14:15], 0
	s_branch .LBB0_2332
